# diff-attention epilogue: both first-block gate-load batches issued before a single wait
# baseline (speedup 1.0000x reference)
; __device__ __forceinline__ int crow(int r, int hi) { return (r & 3) + 8 * (r >> 2) + 4 * hi; }
; #define ATT_SB() __builtin_amdgcn_sched_barrier(0)
; #define ATT_VREAD(buf, ks, vso) do { _Pragma("unroll") for (int d0 = 0; d0 < ND; ++d0) { const lds_cptr vq_ = ((d0 & 1) ? vpo : vpe) + (vso) + (d0 >> 1) * 8192 + (ks) * 2048; \
;       const s16x4 lo = vtr(vq_), hi4 = vtr(vq_ + 1024); \
;       buf[d0] = (bf16x8){lo[0], lo[1], lo[2], lo[3], hi4[0], hi4[1], hi4[2], hi4[3]}; } } while (0)
; #define ATT_PV_REST(vp) do { ATT_PVK_RD(vA, 0, vp); ATT_PVK_RD(vB, 1, vp); ATT_PVK(vA, 2); ATT_PVK(vB, 3); } while (0)
; template <int MODE>
; __device__ __forceinline__ void attn_unit(const Tensors& T0, int ureq, int b, int hh, int qblk, LAS3 char* shm, const bool dummy = false) {
;     ...
;   { const int vp = ((NT - 1) & 3) * SLOTB; ATT_VREAD(vB, 1, vp); ATT_SB(); ATT_PV_REST(vp); }
;     ...
;   { auto rr = __builtin_amdgcn_permlane32_swap(__float_as_uint(l_reg), __float_as_uint(l_reg), false, false); l_reg = __uint_as_float(rr[0]) + __uint_as_float(rr[1]); }
;   if (hi == 0) wsf[32 + r32] = l_reg;
;   asm volatile("s_waitcnt lgkmcnt(0)" ::: "memory");
;   float rli[16];
; #pragma unroll
;   for (int r = 0; r < 16; ++r) rli[r] = 1.0f / wsf[32 + crow(r, hi)];
;   if (MODE) {
;     bf16_t* const gpb = T.G + (size_t)(rowbase + q0w) * 2048 + 1024 + hh * 128 + r32;
;     bf16_t gv[2][16];
;     if (sub == 0 && !dummy) {
; #pragma unroll
;       for (int r = 0; r < 16; ++r) gv[0][r] = gpb[(size_t)crow(r, hi) * 2048]; }
.LBB0_136:
	s_setprio 0
	v_add_u32_e32 v80, 0x1c800, v193
	v_add_u32_e32 v82, 0x1cc00, v193
	v_add_u32_e32 v84, 0x1c800, v190
	v_add_u32_e32 v86, 0x1cc00, v190
	v_add_u32_e32 v88, 0x1e800, v193
	v_add_u32_e32 v90, 0x1ec00, v193
	v_add_u32_e32 v92, 0x1e800, v190
	v_add_u32_e32 v94, 0x1ec00, v190
	ds_read_b64_tr_b16 v[80:81], v80
	ds_read_b64_tr_b16 v[82:83], v82
	ds_read_b64_tr_b16 v[84:85], v84
	ds_read_b64_tr_b16 v[86:87], v86
	ds_read_b64_tr_b16 v[88:89], v88
	ds_read_b64_tr_b16 v[90:91], v90
	ds_read_b64_tr_b16 v[92:93], v92
	ds_read_b64_tr_b16 v[94:95], v94
	s_waitcnt lgkmcnt(14)
	v_mfma_f32_32x32x16_bf16 v[48:63], v[96:99], v[156:159], v[48:63]
	v_add_u32_e32 v100, 0x1d000, v193
	v_add_u32_e32 v102, 0x1d400, v193
	ds_read_b64_tr_b16 v[100:101], v100
	ds_read_b64_tr_b16 v[102:103], v102
	s_waitcnt lgkmcnt(12)
	v_mfma_f32_32x32x16_bf16 v[64:79], v[96:99], v[152:155], v[64:79]
	v_add_u32_e32 v104, 0x1d000, v190
	v_add_u32_e32 v106, 0x1d400, v190
	ds_read_b64_tr_b16 v[104:105], v104
	ds_read_b64_tr_b16 v[106:107], v106
	v_mfma_f32_32x32x16_bf16 v[32:47], v[96:99], v[148:151], v[32:47]
	v_add_u32_e32 v108, 0x1f000, v193
	v_add_u32_e32 v110, 0x1f400, v193
	ds_read_b64_tr_b16 v[108:109], v108
	ds_read_b64_tr_b16 v[110:111], v110
	s_waitcnt lgkmcnt(14)
	v_mfma_f32_32x32x16_bf16 v[16:31], v[96:99], v[144:147], v[16:31]
	v_add_u32_e32 v112, 0x1f000, v190
	v_add_u32_e32 v114, 0x1f400, v190
	ds_read_b64_tr_b16 v[112:113], v112
	ds_read_b64_tr_b16 v[114:115], v114
	s_waitcnt lgkmcnt(14)
	v_mfma_f32_32x32x16_bf16 v[48:63], v[168:171], v[80:83], v[48:63]
	v_add_u32_e32 v96, 0x1d800, v193
	v_add_u32_e32 v98, 0x1dc00, v193
	ds_read_b64_tr_b16 v[96:97], v96
	ds_read_b64_tr_b16 v[98:99], v98
	s_waitcnt lgkmcnt(14)
	v_mfma_f32_32x32x16_bf16 v[64:79], v[168:171], v[84:87], v[64:79]
	v_add_u32_e32 v80, 0x1d800, v190
	v_add_u32_e32 v82, 0x1dc00, v190
	ds_read_b64_tr_b16 v[80:81], v80
	ds_read_b64_tr_b16 v[82:83], v82
	s_waitcnt lgkmcnt(14)
	v_mfma_f32_32x32x16_bf16 v[32:47], v[168:171], v[88:91], v[32:47]
	v_add_u32_e32 v84, 0x1f800, v193
	v_add_u32_e32 v86, 0x1fc00, v193
	ds_read_b64_tr_b16 v[84:85], v84
	ds_read_b64_tr_b16 v[86:87], v86
	s_waitcnt lgkmcnt(14)
	v_mfma_f32_32x32x16_bf16 v[16:31], v[168:171], v[92:95], v[16:31]
	v_add_u32_e32 v88, 0x1f800, v190
	v_add_u32_e32 v90, 0x1fc00, v190
	ds_read_b64_tr_b16 v[88:89], v88
	ds_read_b64_tr_b16 v[90:91], v90
	s_waitcnt lgkmcnt(14)
	v_mfma_f32_32x32x16_bf16 v[48:63], v[164:167], v[100:103], v[48:63]
	s_waitcnt lgkmcnt(12)
	v_mfma_f32_32x32x16_bf16 v[64:79], v[164:167], v[104:107], v[64:79]
	s_waitcnt lgkmcnt(10)
	v_mfma_f32_32x32x16_bf16 v[32:47], v[164:167], v[108:111], v[32:47]
	s_waitcnt lgkmcnt(8)
	v_mfma_f32_32x32x16_bf16 v[16:31], v[164:167], v[112:115], v[16:31]
	s_waitcnt lgkmcnt(6)
	v_mfma_f32_32x32x16_bf16 v[48:63], v[160:163], v[96:99], v[48:63]
	s_waitcnt lgkmcnt(4)
	v_mfma_f32_32x32x16_bf16 v[64:79], v[160:163], v[80:83], v[64:79]
	v_mov_b32_e32 v80, v198
	s_nop 1
	v_permlane32_swap_b32_e32 v198, v80
	s_waitcnt lgkmcnt(2)
	v_mfma_f32_32x32x16_bf16 v[32:47], v[160:163], v[84:87], v[32:47]
	s_waitcnt lgkmcnt(0)
	v_mfma_f32_32x32x16_bf16 v[16:31], v[160:163], v[88:91], v[16:31]
	s_and_saveexec_b64 s[4:5], s[6:7]
	v_add_f32_e32 v80, v198, v80
	ds_write_b32 v200, v80 offset:128
	s_or_b64 exec, exec, s[4:5]
	s_waitcnt lgkmcnt(0)
	ds_read_b128 v[92:95], v199 offset:128
	ds_read_b128 v[88:91], v199 offset:160
	ds_read_b128 v[84:87], v199 offset:192
	ds_read_b128 v[80:83], v199 offset:224
	s_lshl_b64 s[4:5], s[74:75], 12
	s_add_u32 s4, s50, s4
	s_addc_u32 s5, s51, s5
	s_lshl_b32 s6, s80, 1
	s_add_u32 s4, s4, s6
	s_addc_u32 s5, s5, 0
	v_lshlrev_b32_e32 v174, 1, v186
	s_cmpk_lt_u32 s91, 0x100
	v_lshl_add_u64 v[96:97], s[4:5], 0, v[174:175]
	v_mov_b32_e32 v98, 0
	s_cselect_b64 s[4:5], -1, 0
	s_cmpk_gt_u32 s91, 0xff
	v_lshlrev_b32_e32 v174, 14, v188
	v_mov_b32_e32 v99, 0
	v_mov_b32_e32 v100, 0
	v_mov_b32_e32 v101, 0
	v_mov_b32_e32 v102, 0
	v_mov_b32_e32 v103, 0
	v_mov_b32_e32 v104, 0
	v_mov_b32_e32 v105, 0
	v_mov_b32_e32 v106, 0
	v_mov_b32_e32 v107, 0
	v_mov_b32_e32 v108, 0
	v_mov_b32_e32 v109, 0
	v_mov_b32_e32 v121, 0
	v_mov_b32_e32 v123, 0
	v_mov_b32_e32 v125, 0
	v_mov_b32_e32 v177, 0
	s_cbranch_scc1 .LBB0_140
	v_lshl_add_u64 v[98:99], v[96:97], 0, v[174:175]
	v_add_co_u32_e32 v100, vcc, 0x1000, v98
	s_nop 1
	v_addc_co_u32_e32 v101, vcc, 0, v99, vcc
	v_add_co_u32_e32 v102, vcc, 0x2000, v98
	s_nop 1
	v_addc_co_u32_e32 v103, vcc, 0, v99, vcc
	v_add_co_u32_e32 v104, vcc, 0x3000, v98
	s_nop 1
	v_addc_co_u32_e32 v105, vcc, 0, v99, vcc
	v_add_co_u32_e32 v106, vcc, 0x8000, v98
	s_nop 1
	v_addc_co_u32_e32 v107, vcc, 0, v99, vcc
	v_add_co_u32_e32 v108, vcc, s85, v98
	s_nop 1
	v_addc_co_u32_e32 v109, vcc, 0, v99, vcc
	v_add_co_u32_e32 v110, vcc, 0xa000, v98
	s_nop 1
	v_addc_co_u32_e32 v111, vcc, 0, v99, vcc
	v_add_co_u32_e32 v112, vcc, 0xb000, v98
	s_nop 1
	v_addc_co_u32_e32 v113, vcc, 0, v99, vcc
	flat_load_ushort v114, v[100:101] offset:2048
	flat_load_ushort v115, v[102:103] offset:2048
	flat_load_ushort v116, v[104:105] offset:2048
	flat_load_ushort v117, v[106:107] offset:2048
	flat_load_ushort v118, v[108:109] offset:2048
	flat_load_ushort v119, v[110:111] offset:2048
	flat_load_ushort v120, v[112:113] offset:2048
	flat_load_ushort v121, v[98:99] offset:2048
	v_add_co_u32_e32 v100, vcc, 0x10000, v98
	s_nop 1
	v_addc_co_u32_e32 v101, vcc, 0, v99, vcc
	v_add_co_u32_e32 v102, vcc, 0x11000, v98
	s_nop 0
	s_nop 0
	v_addc_co_u32_e32 v103, vcc, 0, v99, vcc
	v_add_co_u32_e32 v104, vcc, 0x12000, v98
	s_nop 0
	s_nop 0
	v_addc_co_u32_e32 v105, vcc, 0, v99, vcc
	v_add_co_u32_e32 v106, vcc, 0x13000, v98
	s_nop 0
	s_nop 0
	v_addc_co_u32_e32 v107, vcc, 0, v99, vcc
	v_add_co_u32_e32 v108, vcc, 0x18000, v98
	s_nop 1
	v_addc_co_u32_e32 v109, vcc, 0, v99, vcc
	v_add_co_u32_e32 v110, vcc, 0x19000, v98
	s_nop 1
	v_addc_co_u32_e32 v111, vcc, 0, v99, vcc
	v_add_co_u32_e32 v112, vcc, 0x1a000, v98
	s_nop 1
	v_addc_co_u32_e32 v113, vcc, 0, v99, vcc
	v_add_co_u32_e32 v98, vcc, 0x1b000, v98
	flat_load_ushort v102, v[102:103] offset:2048
	s_nop 0
	flat_load_ushort v103, v[106:107] offset:2048
	s_nop 0
	flat_load_ushort v110, v[110:111] offset:2048
	s_nop 0
	flat_load_ushort v111, v[112:113] offset:2048
	s_nop 0
	flat_load_ushort v112, v[108:109] offset:2048
	flat_load_ushort v113, v[104:105] offset:2048
	s_nop 0
	flat_load_ushort v100, v[100:101] offset:2048
	v_addc_co_u32_e32 v99, vcc, 0, v99, vcc
	flat_load_ushort v98, v[98:99] offset:2048
	s_waitcnt vmcnt(0) lgkmcnt(0)
	v_lshlrev_b32_e32 v125, 16, v114
	v_lshlrev_b32_e32 v123, 16, v115
	v_lshlrev_b32_e32 v177, 16, v121
	v_lshlrev_b32_e32 v121, 16, v116
	v_lshlrev_b32_e32 v108, 16, v118
	v_lshlrev_b32_e32 v109, 16, v117
	v_lshlrev_b32_e32 v106, 16, v120
	v_lshlrev_b32_e32 v107, 16, v119
	v_lshlrev_b32_e32 v104, 16, v102
	v_lshlrev_b32_e32 v102, 16, v103
	v_lshlrev_b32_e32 v99, 16, v111
	v_lshlrev_b32_e32 v101, 16, v112
	v_lshlrev_b32_e32 v103, 16, v113
	v_lshlrev_b32_e32 v105, 16, v100
	v_lshlrev_b32_e32 v100, 16, v110
	v_lshlrev_b32_e32 v98, 16, v98
